# v80 + second half of each step's row sum added in the P.V MFMA gaps (same summation order), 8 fewer VALU per step in the softmax block
# baseline (speedup 1.0000x reference)
; #define SBAR() __builtin_amdgcn_sched_barrier(0)
; #define ATT_DMA_K(t) do { const bf16_t* kg_ = Kh + (size_t)(t) * 64 * LDK; LAS unsigned char* sb_ = lds + ((t) & 3) * KBUF; \
;     _Pragma("unroll") for (int i_ = 0; i_ < NKP; ++i_) __builtin_amdgcn_global_load_lds((const unsigned*)(kg_ + kgo[i_]), (LAS unsigned*)(sb_ + (wid + 8 * i_) * 1024), 16, 0, 0); } while (0)
; #define ATT_DMA_V(t, vs) do { const bf16_t* vg_ = Vh + (size_t)(t) * 64 * LDV; LAS unsigned char* sb_ = lds + V_OFF + (vs) * SHM_V; \
;     _Pragma("unroll") for (int i_ = 0; i_ < 2; ++i_) __builtin_amdgcn_global_load_lds((const unsigned*)(vg_ + vgo[i_]), (LAS unsigned*)(sb_ + (2 * wid + i_) * 1024), 16, 0, 0); } while (0)
; #define ATT_SEG(t) do { if constexpr (MODE != 0) { if (((t) == tL && tL > 0) || (t) == tR) { const float f_ = (t) == tR ? fR : fL; l_reg *= f_; \
;     _Pragma("unroll") for (int d = 0; d < 4; ++d) _Pragma("unroll") for (int r = 0; r < 16; ++r) o[d][r] *= f_; } } } while (0)
; #define ATT_TOP(N) do { asm volatile("s_waitcnt vmcnt(%0)" :: "n"(N) : "memory"); __builtin_amdgcn_s_barrier(); asm volatile("" ::: "memory"); } while (0)
; DI void expsum(f32x16& p, float& l_reg, bf16x8& pa0, bf16x8& pa1) {
; #pragma unroll
;     for (int r = 0; r < 16; ++r) p[r] = __builtin_amdgcn_exp2f(p[r]);
;     float ps = 0.f;
; #pragma unroll
;     for (int r = 0; r < 16; ++r) ps += p[r];
;     l_reg += ps; asm volatile("" : "+v"(l_reg));
;     ...
;     ATT_PK4(p, 0, pa0); ATT_PK4(p, 8, pa1);
;     ...
; }
; template <int DQK, int MODE, int LDQ, int LDK, int LDV> ...
;     ...
;     f32x16 pA, pB; bf16x8 pa0, pa1;
;     int v0 = 0, v1 = 1, v2 = 2;
;     ATT_TOP(NKP + 2);
;     { bf16x8 kf[NDA]; k_reads<DQK, 0, NDA>(kf, lds, 0, r32, hi); ATT_LGKM0(); qk_mma<0, NDA>(pA, kf, qr);
;       if constexpr (ND0 > NDA) { bf16x8 kg[ND0 - NDA]; k_reads<DQK, NDA, ND0>(kg, lds, 0, r32, hi); ATT_LGKM0(); qk_mma<NDA, ND0>(pA, kg, qr); }
;       ATT_BIAS(pA, 0, 0); }
;     if (wid >= 4) __builtin_amdgcn_s_setprio(1);
;     for (int j = 0; j < NT; ++j) {
;         if (j + 2 < NT) ATT_TOP(NKP + 2); else ATT_TOP(0);
;         if (j + 3 < NT) ATT_DMA_K(j + 3);
;         if (j + 2 < NT) ATT_DMA_V(j + 2, v2);
;         ATT_SEG(j); SBAR();
;         ATT_STEP(pA, pB, 0, v0, true, 1, j);
;         ATT_STEP(pB, pA, 1, v0, (j + 1 < NT), 0, j + 1);
;         { const int t_ = v0; v0 = v1; v1 = v2; v2 = t_; }
;     }
.Lhw_d0_b_n1922:
	ds_read_b128 v[122:125], v196 offset:4096
	ds_read_b128 v[132:135], v197 offset:4096
	s_lshl_b32 s2, s1, 14
	ds_read_b128 v[136:139], v198 offset:4096
	ds_read_b128 v[140:143], v199 offset:4096
	v_add_u32_e32 v121, s2, v106
	ds_read_b64_tr_b16 v[144:145], v121 offset:0
	ds_read_b64_tr_b16 v[146:147], v121 offset:0x800
	ds_read_b64_tr_b16 v[148:149], v121 offset:0x1000
	ds_read_b64_tr_b16 v[150:151], v121 offset:0x1800
	ds_read_b64_tr_b16 v[152:153], v121 offset:0x200
	ds_read_b64_tr_b16 v[154:155], v121 offset:0xa00
	ds_read_b64_tr_b16 v[156:157], v121 offset:0x1200
	ds_read_b64_tr_b16 v[158:159], v121 offset:0x1a00
	ds_read_b64_tr_b16 v[162:163], v121 offset:0x400
	ds_read_b64_tr_b16 v[164:165], v121 offset:0xc00
	ds_read_b64_tr_b16 v[166:167], v121 offset:0x1400
	ds_read_b64_tr_b16 v[168:169], v121 offset:0x1c00
	ds_read_b64_tr_b16 v[170:171], v121 offset:0x600
	ds_read_b64_tr_b16 v[172:173], v121 offset:0xe00
	ds_read_b64_tr_b16 v[174:175], v121 offset:0x1600
	ds_read_b64_tr_b16 v[176:177], v121 offset:0x1e00
	s_setprio 1
	v_exp_f32_e32 v64, v64
	v_exp_f32_e32 v65, v65
	v_exp_f32_e32 v66, v66
	v_exp_f32_e32 v67, v67
	v_exp_f32_e32 v68, v68
	v_exp_f32_e32 v69, v69
	v_add_f32_e32 v126, v65, v64
	v_exp_f32_e32 v70, v70
	v_add_f32_e32 v126, v66, v126
	v_exp_f32_e32 v71, v71
	v_add_f32_e32 v126, v67, v126
	v_exp_f32_e32 v72, v72
	v_add_f32_e32 v126, v68, v126
	v_exp_f32_e32 v73, v73
	v_add_f32_e32 v126, v69, v126
	v_exp_f32_e32 v74, v74
	v_add_f32_e32 v126, v70, v126
	v_exp_f32_e32 v75, v75
	v_add_f32_e32 v126, v71, v126
	v_exp_f32_e32 v76, v76
	v_exp_f32_e32 v77, v77
	v_exp_f32_e32 v78, v78
	v_exp_f32_e32 v79, v79
	v_cvt_pk_bf16_f32 v64, v64, v65
	v_cvt_pk_bf16_f32 v65, v66, v67
	v_cvt_pk_bf16_f32 v66, v68, v69
	v_cvt_pk_bf16_f32 v67, v70, v71
	v_cvt_pk_bf16_f32 v68, v72, v73
	v_cvt_pk_bf16_f32 v69, v74, v75
	v_cvt_pk_bf16_f32 v70, v76, v77
	v_cvt_pk_bf16_f32 v71, v78, v79
	v_add_f32_e32 v72, v72, v126
	s_waitcnt lgkmcnt(0)
	s_setprio 2
	v_mfma_f32_32x32x16_bf16 v[0:15], v[64:67], v[144:147], v[0:15]
	v_add_f32_e32 v72, v73, v72
	s_sub_i32 s3, s0, s98
	s_cmp_lt_u32 s3, s100
	v_mfma_f32_32x32x16_bf16 v[48:63], v[64:67], v[152:155], v[48:63]
	v_add_f32_e32 v72, v74, v72
	v_mfma_f32_32x32x16_bf16 v[32:47], v[64:67], v[162:165], v[32:47]
	v_add_f32_e32 v72, v75, v72
	v_mfma_f32_32x32x16_bf16 v[16:31], v[64:67], v[170:173], v[16:31]
	v_add_f32_e32 v72, v76, v72
	v_mfma_f32_32x32x16_bf16 v[0:15], v[68:71], v[148:151], v[0:15]
	v_add_f32_e32 v72, v77, v72
	v_mfma_f32_32x32x16_bf16 v[48:63], v[68:71], v[156:159], v[48:63]
	v_add_f32_e32 v72, v78, v72
	v_mfma_f32_32x32x16_bf16 v[32:47], v[68:71], v[166:169], v[32:47]
	v_add_f32_e32 v72, v79, v72
	v_mfma_f32_32x32x16_bf16 v[16:31], v[68:71], v[174:177], v[16:31]
	v_add_f32_e32 v120, v120, v72
	v_mfma_f32_32x32x16_bf16 v[64:79], v[122:125], v[92:95], 0
	v_mfma_f32_32x32x16_bf16 v[64:79], v[132:135], v[88:91], v[64:79]
	v_mfma_f32_32x32x16_bf16 v[64:79], v[136:139], v[84:87], v[64:79]
	v_mfma_f32_32x32x16_bf16 v[64:79], v[140:143], v[80:83], v[64:79]
	s_setprio 0
	s_cbranch_scc1 .Lhw_d0_b_dtd0bias1
.Lhw_d0_b_n1924:
	s_add_i32 s3, s22, 0xffffc000
	s_and_b32 s3, s3, 0x6000
	v_add_u32_e32 v196, s3, v107
	v_add_u32_e32 v197, s3, v108
	v_add_u32_e32 v198, s3, v109
	v_add_u32_e32 v199, s3, v110
	ds_read_b128 v[124:127], v196
	ds_read_b128 v[132:135], v197
	ds_read_b128 v[136:139], v198
	ds_read_b128 v[140:143], v199
	ds_read_b64_tr_b16 v[144:145], v121 offset:0x2000
	ds_read_b64_tr_b16 v[146:147], v121 offset:0x2800
	ds_read_b64_tr_b16 v[148:149], v121 offset:0x3000
	ds_read_b64_tr_b16 v[150:151], v121 offset:0x3800
	ds_read_b64_tr_b16 v[152:153], v121 offset:0x2200
	ds_read_b64_tr_b16 v[154:155], v121 offset:0x2a00
	ds_read_b64_tr_b16 v[156:157], v121 offset:0x3200
	ds_read_b64_tr_b16 v[158:159], v121 offset:0x3a00
	ds_read_b64_tr_b16 v[162:163], v121 offset:0x2400
	ds_read_b64_tr_b16 v[164:165], v121 offset:0x2c00
	ds_read_b64_tr_b16 v[166:167], v121 offset:0x3400
	ds_read_b64_tr_b16 v[168:169], v121 offset:0x3c00
	ds_read_b64_tr_b16 v[170:171], v121 offset:0x2600
	ds_read_b64_tr_b16 v[172:173], v121 offset:0x2e00
	ds_read_b64_tr_b16 v[174:175], v121 offset:0x3600
	ds_read_b64_tr_b16 v[176:177], v121 offset:0x3e00
	s_setprio 1
	v_exp_f32_e32 v64, v64
	v_exp_f32_e32 v65, v65
	v_exp_f32_e32 v66, v66
	v_exp_f32_e32 v67, v67
	v_exp_f32_e32 v68, v68
	v_exp_f32_e32 v69, v69
	v_add_f32_e32 v121, v65, v64
	v_exp_f32_e32 v70, v70
	v_add_f32_e32 v121, v66, v121
	v_exp_f32_e32 v71, v71
	v_add_f32_e32 v121, v67, v121
	v_exp_f32_e32 v72, v72
	v_add_f32_e32 v121, v68, v121
	v_exp_f32_e32 v73, v73
	v_add_f32_e32 v121, v69, v121
	v_exp_f32_e32 v74, v74
	v_add_f32_e32 v121, v70, v121
	v_exp_f32_e32 v75, v75
	v_add_f32_e32 v121, v71, v121
	v_exp_f32_e32 v76, v76
	v_exp_f32_e32 v77, v77
	v_exp_f32_e32 v78, v78
	v_exp_f32_e32 v79, v79
	v_cvt_pk_bf16_f32 v64, v64, v65
	v_cvt_pk_bf16_f32 v65, v66, v67
	v_cvt_pk_bf16_f32 v66, v68, v69
	v_cvt_pk_bf16_f32 v67, v70, v71
	v_cvt_pk_bf16_f32 v68, v72, v73
	v_cvt_pk_bf16_f32 v69, v74, v75
	v_cvt_pk_bf16_f32 v70, v76, v77
	v_cvt_pk_bf16_f32 v71, v78, v79
	v_add_f32_e32 v72, v72, v121
	s_waitcnt lgkmcnt(0)
	s_setprio 2
	s_waitcnt vmcnt(3)
	s_barrier
	v_mfma_f32_32x32x16_bf16 v[0:15], v[64:67], v[144:147], v[0:15]
	v_add_f32_e32 v72, v73, v72
	s_sub_i32 s74, s0, s55
	s_cmp_lt_u32 s74, s100
	v_mfma_f32_32x32x16_bf16 v[48:63], v[64:67], v[152:155], v[48:63]
	v_add_f32_e32 v72, v74, v72
	v_mfma_f32_32x32x16_bf16 v[32:47], v[64:67], v[162:165], v[32:47]
	v_add_f32_e32 v72, v75, v72
	v_mfma_f32_32x32x16_bf16 v[16:31], v[64:67], v[170:173], v[16:31]
	v_add_f32_e32 v72, v76, v72
	v_mfma_f32_32x32x16_bf16 v[0:15], v[68:71], v[148:151], v[0:15]
	v_add_f32_e32 v72, v77, v72
	v_mfma_f32_32x32x16_bf16 v[48:63], v[68:71], v[156:159], v[48:63]
	v_add_f32_e32 v72, v78, v72
	v_mfma_f32_32x32x16_bf16 v[32:47], v[68:71], v[166:169], v[32:47]
	v_add_f32_e32 v72, v79, v72
	v_mfma_f32_32x32x16_bf16 v[16:31], v[68:71], v[174:177], v[16:31]
	v_add_f32_e32 v120, v120, v72
	v_mfma_f32_32x32x16_bf16 v[64:79], v[124:127], v[92:95], 0
	v_mfma_f32_32x32x16_bf16 v[64:79], v[132:135], v[88:91], v[64:79]
	v_mfma_f32_32x32x16_bf16 v[64:79], v[136:139], v[84:87], v[64:79]
	v_mfma_f32_32x32x16_bf16 v[64:79], v[140:143], v[80:83], v[64:79]
	s_cbranch_scc1 .Lhw_d0_b_dtd0bias2

; #define SBAR() __builtin_amdgcn_sched_barrier(0)
; #define ATT_DMA_K(t) do { const bf16_t* kg_ = Kh + (size_t)(t) * 64 * LDK; LAS unsigned char* sb_ = lds + ((t) & 3) * KBUF; \
;     _Pragma("unroll") for (int i_ = 0; i_ < NKP; ++i_) __builtin_amdgcn_global_load_lds((const unsigned*)(kg_ + kgo[i_]), (LAS unsigned*)(sb_ + (wid + 8 * i_) * 1024), 16, 0, 0); } while (0)
; #define ATT_DMA_V(t, vs) do { const bf16_t* vg_ = Vh + (size_t)(t) * 64 * LDV; LAS unsigned char* sb_ = lds + V_OFF + (vs) * SHM_V; \
;     _Pragma("unroll") for (int i_ = 0; i_ < 2; ++i_) __builtin_amdgcn_global_load_lds((const unsigned*)(vg_ + vgo[i_]), (LAS unsigned*)(sb_ + (2 * wid + i_) * 1024), 16, 0, 0); } while (0)
; #define ATT_SEG(t) do { if constexpr (MODE != 0) { if (((t) == tL && tL > 0) || (t) == tR) { const float f_ = (t) == tR ? fR : fL; l_reg *= f_; \
;     _Pragma("unroll") for (int d = 0; d < 4; ++d) _Pragma("unroll") for (int r = 0; r < 16; ++r) o[d][r] *= f_; } } } while (0)
; #define ATT_TOP(N) do { asm volatile("s_waitcnt vmcnt(%0)" :: "n"(N) : "memory"); __builtin_amdgcn_s_barrier(); asm volatile("" ::: "memory"); } while (0)
; DI void expsum(f32x16& p, float& l_reg, bf16x8& pa0, bf16x8& pa1) {
; #pragma unroll
;     for (int r = 0; r < 16; ++r) p[r] = __builtin_amdgcn_exp2f(p[r]);
;     float ps = 0.f;
; #pragma unroll
;     for (int r = 0; r < 16; ++r) ps += p[r];
;     l_reg += ps; asm volatile("" : "+v"(l_reg));
;     ...
;     ATT_PK4(p, 0, pa0); ATT_PK4(p, 8, pa1);
;     ...
; }
; template <int DQK, int MODE, int LDQ, int LDK, int LDV> ...
;     ...
;     f32x16 pA, pB; bf16x8 pa0, pa1;
;     int v0 = 0, v1 = 1, v2 = 2;
;     ATT_TOP(NKP + 2);
;     { bf16x8 kf[NDA]; k_reads<DQK, 0, NDA>(kf, lds, 0, r32, hi); ATT_LGKM0(); qk_mma<0, NDA>(pA, kf, qr);
;       if constexpr (ND0 > NDA) { bf16x8 kg[ND0 - NDA]; k_reads<DQK, NDA, ND0>(kg, lds, 0, r32, hi); ATT_LGKM0(); qk_mma<NDA, ND0>(pA, kg, qr); }
;       ATT_BIAS(pA, 0, 0); }
;     if (wid >= 4) __builtin_amdgcn_s_setprio(1);
;     for (int j = 0; j < NT; ++j) {
;         if (j + 2 < NT) ATT_TOP(NKP + 2); else ATT_TOP(0);
;         if (j + 3 < NT) ATT_DMA_K(j + 3);
;         if (j + 2 < NT) ATT_DMA_V(j + 2, v2);
;         ATT_SEG(j); SBAR();
;         ATT_STEP(pA, pB, 0, v0, true, 1, j);
;         ATT_STEP(pB, pA, 1, v0, (j + 1 < NT), 0, j + 1);
;         { const int t_ = v0; v0 = v1; v1 = v2; v2 = t_; }
;     }
.LBB0_1924:
	s_add_i32 s3, s22, 0xffffc000
	s_and_b32 s3, s3, 0x6000
	v_add_u32_e32 v196, s3, v107
	v_add_u32_e32 v197, s3, v108
	v_add_u32_e32 v198, s3, v109
	v_add_u32_e32 v199, s3, v110
	ds_read_b128 v[124:127], v196
	ds_read_b128 v[132:135], v197
	ds_read_b128 v[136:139], v198
	ds_read_b128 v[140:143], v199
	ds_read_b64_tr_b16 v[144:145], v121 offset:0x2000
	ds_read_b64_tr_b16 v[146:147], v121 offset:0x2800
	ds_read_b64_tr_b16 v[148:149], v121 offset:0x3000
	ds_read_b64_tr_b16 v[150:151], v121 offset:0x3800
	ds_read_b64_tr_b16 v[152:153], v121 offset:0x2200
	ds_read_b64_tr_b16 v[154:155], v121 offset:0x2a00
	ds_read_b64_tr_b16 v[156:157], v121 offset:0x3200
	ds_read_b64_tr_b16 v[158:159], v121 offset:0x3a00
	ds_read_b64_tr_b16 v[162:163], v121 offset:0x2400
	ds_read_b64_tr_b16 v[164:165], v121 offset:0x2c00
	ds_read_b64_tr_b16 v[166:167], v121 offset:0x3400
	ds_read_b64_tr_b16 v[168:169], v121 offset:0x3c00
	ds_read_b64_tr_b16 v[170:171], v121 offset:0x2600
	ds_read_b64_tr_b16 v[172:173], v121 offset:0x2e00
	ds_read_b64_tr_b16 v[174:175], v121 offset:0x3600
	ds_read_b64_tr_b16 v[176:177], v121 offset:0x3e00
	s_setprio 1
	v_exp_f32_e32 v64, v64
	v_exp_f32_e32 v65, v65
	v_exp_f32_e32 v66, v66
	v_exp_f32_e32 v67, v67
	v_exp_f32_e32 v68, v68
	v_exp_f32_e32 v69, v69
	v_add_f32_e32 v121, v65, v64
	v_exp_f32_e32 v70, v70
	v_add_f32_e32 v121, v66, v121
	v_exp_f32_e32 v71, v71
	v_add_f32_e32 v121, v67, v121
	v_exp_f32_e32 v72, v72
	v_add_f32_e32 v121, v68, v121
	v_exp_f32_e32 v73, v73
	v_add_f32_e32 v121, v69, v121
	v_exp_f32_e32 v74, v74
	v_add_f32_e32 v121, v70, v121
	v_exp_f32_e32 v75, v75
	v_add_f32_e32 v121, v71, v121
	v_exp_f32_e32 v76, v76
	v_exp_f32_e32 v77, v77
	v_exp_f32_e32 v78, v78
	v_exp_f32_e32 v79, v79
	v_cvt_pk_bf16_f32 v64, v64, v65
	v_cvt_pk_bf16_f32 v65, v66, v67
	v_cvt_pk_bf16_f32 v66, v68, v69
	v_cvt_pk_bf16_f32 v67, v70, v71
	v_cvt_pk_bf16_f32 v68, v72, v73
	v_cvt_pk_bf16_f32 v69, v74, v75
	v_cvt_pk_bf16_f32 v70, v76, v77
	v_cvt_pk_bf16_f32 v71, v78, v79
	v_add_f32_e32 v72, v72, v121
	s_waitcnt lgkmcnt(0)
	s_setprio 2
	v_mfma_f32_32x32x16_bf16 v[0:15], v[64:67], v[144:147], v[0:15]
	v_add_f32_e32 v72, v73, v72
	s_sub_i32 s74, s0, s55
	s_cmp_lt_u32 s74, s100
	v_mfma_f32_32x32x16_bf16 v[48:63], v[64:67], v[152:155], v[48:63]
	v_add_f32_e32 v72, v74, v72
	v_mfma_f32_32x32x16_bf16 v[32:47], v[64:67], v[162:165], v[32:47]
	v_add_f32_e32 v72, v75, v72
	v_mfma_f32_32x32x16_bf16 v[16:31], v[64:67], v[170:173], v[16:31]
	v_add_f32_e32 v72, v76, v72
	v_mfma_f32_32x32x16_bf16 v[0:15], v[68:71], v[148:151], v[0:15]
	v_add_f32_e32 v72, v77, v72
	v_mfma_f32_32x32x16_bf16 v[48:63], v[68:71], v[156:159], v[48:63]
	v_add_f32_e32 v72, v78, v72
	v_mfma_f32_32x32x16_bf16 v[32:47], v[68:71], v[166:169], v[32:47]
	v_add_f32_e32 v72, v79, v72
	v_mfma_f32_32x32x16_bf16 v[16:31], v[68:71], v[174:177], v[16:31]
	v_add_f32_e32 v120, v120, v72
	v_mfma_f32_32x32x16_bf16 v[64:79], v[124:127], v[92:95], 0
	v_mfma_f32_32x32x16_bf16 v[64:79], v[132:135], v[88:91], v[64:79]
	v_mfma_f32_32x32x16_bf16 v[64:79], v[136:139], v[84:87], v[64:79]
	v_mfma_f32_32x32x16_bf16 v[64:79], v[140:143], v[80:83], v[64:79]
	s_cbranch_scc1 .Ldt_d0_bias2

; #define SBAR() __builtin_amdgcn_sched_barrier(0)
; #define ATT_DMA_K(t) do { const bf16_t* kg_ = Kh + (size_t)(t) * 64 * LDK; LAS unsigned char* sb_ = lds + ((t) & 3) * KBUF; \
;     _Pragma("unroll") for (int i_ = 0; i_ < NKP; ++i_) __builtin_amdgcn_global_load_lds((const unsigned*)(kg_ + kgo[i_]), (LAS unsigned*)(sb_ + (wid + 8 * i_) * 1024), 16, 0, 0); } while (0)
; #define ATT_DMA_V(t, vs) do { const bf16_t* vg_ = Vh + (size_t)(t) * 64 * LDV; LAS unsigned char* sb_ = lds + V_OFF + (vs) * SHM_V; \
;     _Pragma("unroll") for (int i_ = 0; i_ < 2; ++i_) __builtin_amdgcn_global_load_lds((const unsigned*)(vg_ + vgo[i_]), (LAS unsigned*)(sb_ + (2 * wid + i_) * 1024), 16, 0, 0); } while (0)
; #define ATT_SEG(t) do { if constexpr (MODE != 0) { if (((t) == tL && tL > 0) || (t) == tR) { const float f_ = (t) == tR ? fR : fL; l_reg *= f_; \
;     _Pragma("unroll") for (int d = 0; d < 4; ++d) _Pragma("unroll") for (int r = 0; r < 16; ++r) o[d][r] *= f_; } } } while (0)
; #define ATT_TOP(N) do { asm volatile("s_waitcnt vmcnt(%0)" :: "n"(N) : "memory"); __builtin_amdgcn_s_barrier(); asm volatile("" ::: "memory"); } while (0)
; DI void expsum(f32x16& p, float& l_reg, bf16x8& pa0, bf16x8& pa1) {
; #pragma unroll
;     for (int r = 0; r < 16; ++r) p[r] = __builtin_amdgcn_exp2f(p[r]);
;     float ps = 0.f;
; #pragma unroll
;     for (int r = 0; r < 16; ++r) ps += p[r];
;     l_reg += ps; asm volatile("" : "+v"(l_reg));
;     ...
;     ATT_PK4(p, 0, pa0); ATT_PK4(p, 8, pa1);
;     ...
; }
; template <int DQK, int MODE, int LDQ, int LDK, int LDV> ...
;     ...
;     f32x16 pA, pB; bf16x8 pa0, pa1;
;     int v0 = 0, v1 = 1, v2 = 2;
;     ATT_TOP(NKP + 2);
;     { bf16x8 kf[NDA]; k_reads<DQK, 0, NDA>(kf, lds, 0, r32, hi); ATT_LGKM0(); qk_mma<0, NDA>(pA, kf, qr);
;       if constexpr (ND0 > NDA) { bf16x8 kg[ND0 - NDA]; k_reads<DQK, NDA, ND0>(kg, lds, 0, r32, hi); ATT_LGKM0(); qk_mma<NDA, ND0>(pA, kg, qr); }
;       ATT_BIAS(pA, 0, 0); }
;     if (wid >= 4) __builtin_amdgcn_s_setprio(1);
;     for (int j = 0; j < NT; ++j) {
;         if (j + 2 < NT) ATT_TOP(NKP + 2); else ATT_TOP(0);
;         if (j + 3 < NT) ATT_DMA_K(j + 3);
;         if (j + 2 < NT) ATT_DMA_V(j + 2, v2);
;         ATT_SEG(j); SBAR();
;         ATT_STEP(pA, pB, 0, v0, true, 1, j);
;         ATT_STEP(pB, pA, 1, v0, (j + 1 < NT), 0, j + 1);
;         { const int t_ = v0; v0 = v1; v1 = v2; v2 = t_; }
;     }
.Lhw_d1_b_n1953:
	ds_read_b128 v[122:125], v196 offset:4096
	ds_read_b128 v[132:135], v197 offset:4096
	s_lshl_b32 s2, s23, 14
	ds_read_b128 v[136:139], v198 offset:4096
	ds_read_b128 v[140:143], v199 offset:4096
	v_add_u32_e32 v121, s2, v106
	ds_read_b64_tr_b16 v[144:145], v121 offset:0
	ds_read_b64_tr_b16 v[146:147], v121 offset:0x800
	ds_read_b64_tr_b16 v[148:149], v121 offset:0x1000
	ds_read_b64_tr_b16 v[150:151], v121 offset:0x1800
	ds_read_b64_tr_b16 v[152:153], v121 offset:0x200
	ds_read_b64_tr_b16 v[154:155], v121 offset:0xa00
	ds_read_b64_tr_b16 v[156:157], v121 offset:0x1200
	ds_read_b64_tr_b16 v[158:159], v121 offset:0x1a00
	ds_read_b64_tr_b16 v[162:163], v121 offset:0x400
	ds_read_b64_tr_b16 v[164:165], v121 offset:0xc00
	ds_read_b64_tr_b16 v[166:167], v121 offset:0x1400
	ds_read_b64_tr_b16 v[168:169], v121 offset:0x1c00
	ds_read_b64_tr_b16 v[170:171], v121 offset:0x600
	ds_read_b64_tr_b16 v[172:173], v121 offset:0xe00
	ds_read_b64_tr_b16 v[174:175], v121 offset:0x1600
	ds_read_b64_tr_b16 v[176:177], v121 offset:0x1e00
	s_setprio 1
	v_exp_f32_e32 v64, v64
	v_exp_f32_e32 v65, v65
	v_exp_f32_e32 v66, v66
	v_exp_f32_e32 v67, v67
	v_exp_f32_e32 v68, v68
	v_exp_f32_e32 v69, v69
	v_add_f32_e32 v126, v65, v64
	v_exp_f32_e32 v70, v70
	v_add_f32_e32 v126, v66, v126
	v_exp_f32_e32 v71, v71
	v_add_f32_e32 v126, v67, v126
	v_exp_f32_e32 v72, v72
	v_add_f32_e32 v126, v68, v126
	v_exp_f32_e32 v73, v73
	v_add_f32_e32 v126, v69, v126
	v_exp_f32_e32 v74, v74
	v_add_f32_e32 v126, v70, v126
	v_exp_f32_e32 v75, v75
	v_add_f32_e32 v126, v71, v126
	v_exp_f32_e32 v76, v76
	v_exp_f32_e32 v77, v77
	v_exp_f32_e32 v78, v78
	v_exp_f32_e32 v79, v79
	v_cvt_pk_bf16_f32 v64, v64, v65
	v_cvt_pk_bf16_f32 v65, v66, v67
	v_cvt_pk_bf16_f32 v66, v68, v69
	v_cvt_pk_bf16_f32 v67, v70, v71
	v_cvt_pk_bf16_f32 v68, v72, v73
	v_cvt_pk_bf16_f32 v69, v74, v75
	v_cvt_pk_bf16_f32 v70, v76, v77
	v_cvt_pk_bf16_f32 v71, v78, v79
	v_add_f32_e32 v72, v72, v126
	s_waitcnt lgkmcnt(0)
	s_setprio 2
	v_mfma_f32_32x32x16_bf16 v[0:15], v[64:67], v[144:147], v[0:15]
	v_add_f32_e32 v72, v73, v72
	s_sub_i32 s3, s0, s98
	s_cmp_lt_u32 s3, s100
	v_mfma_f32_32x32x16_bf16 v[48:63], v[64:67], v[152:155], v[48:63]
	v_add_f32_e32 v72, v74, v72
	v_mfma_f32_32x32x16_bf16 v[16:31], v[64:67], v[162:165], v[16:31]
	v_add_f32_e32 v72, v75, v72
	v_mfma_f32_32x32x16_bf16 v[32:47], v[64:67], v[170:173], v[32:47]
	v_add_f32_e32 v72, v76, v72
	v_mfma_f32_32x32x16_bf16 v[0:15], v[68:71], v[148:151], v[0:15]
	v_add_f32_e32 v72, v77, v72
	v_mfma_f32_32x32x16_bf16 v[48:63], v[68:71], v[156:159], v[48:63]
	v_add_f32_e32 v72, v78, v72
	v_mfma_f32_32x32x16_bf16 v[16:31], v[68:71], v[166:169], v[16:31]
	v_add_f32_e32 v72, v79, v72
	v_mfma_f32_32x32x16_bf16 v[32:47], v[68:71], v[174:177], v[32:47]
	v_add_f32_e32 v120, v120, v72
	v_mfma_f32_32x32x16_bf16 v[64:79], v[122:125], v[92:95], 0
	v_mfma_f32_32x32x16_bf16 v[64:79], v[132:135], v[88:91], v[64:79]
	v_mfma_f32_32x32x16_bf16 v[64:79], v[136:139], v[84:87], v[64:79]
	v_mfma_f32_32x32x16_bf16 v[64:79], v[140:143], v[80:83], v[64:79]
	s_setprio 0
	s_cbranch_scc1 .Lhw_d1_b_dtd1bias1
.Lhw_d1_b_n1955:
	s_add_i32 s3, s22, 0xffffc000
	s_and_b32 s3, s3, 0x6000
	v_add_u32_e32 v196, s3, v107
	v_add_u32_e32 v197, s3, v108
	v_add_u32_e32 v198, s3, v109
	v_add_u32_e32 v199, s3, v110
	ds_read_b128 v[124:127], v196
	ds_read_b128 v[132:135], v197
	ds_read_b128 v[136:139], v198
	ds_read_b128 v[140:143], v199
	ds_read_b64_tr_b16 v[144:145], v121 offset:0x2000
	ds_read_b64_tr_b16 v[146:147], v121 offset:0x2800
	ds_read_b64_tr_b16 v[148:149], v121 offset:0x3000
	ds_read_b64_tr_b16 v[150:151], v121 offset:0x3800
	ds_read_b64_tr_b16 v[152:153], v121 offset:0x2200
	ds_read_b64_tr_b16 v[154:155], v121 offset:0x2a00
	ds_read_b64_tr_b16 v[156:157], v121 offset:0x3200
	ds_read_b64_tr_b16 v[158:159], v121 offset:0x3a00
	ds_read_b64_tr_b16 v[162:163], v121 offset:0x2400
	ds_read_b64_tr_b16 v[164:165], v121 offset:0x2c00
	ds_read_b64_tr_b16 v[166:167], v121 offset:0x3400
	ds_read_b64_tr_b16 v[168:169], v121 offset:0x3c00
	ds_read_b64_tr_b16 v[170:171], v121 offset:0x2600
	ds_read_b64_tr_b16 v[172:173], v121 offset:0x2e00
	ds_read_b64_tr_b16 v[174:175], v121 offset:0x3600
	ds_read_b64_tr_b16 v[176:177], v121 offset:0x3e00
	s_setprio 1
	v_exp_f32_e32 v64, v64
	v_exp_f32_e32 v65, v65
	v_exp_f32_e32 v66, v66
	v_exp_f32_e32 v67, v67
	v_exp_f32_e32 v68, v68
	v_exp_f32_e32 v69, v69
	v_add_f32_e32 v121, v65, v64
	v_exp_f32_e32 v70, v70
	v_add_f32_e32 v121, v66, v121
	v_exp_f32_e32 v71, v71
	v_add_f32_e32 v121, v67, v121
	v_exp_f32_e32 v72, v72
	v_add_f32_e32 v121, v68, v121
	v_exp_f32_e32 v73, v73
	v_add_f32_e32 v121, v69, v121
	v_exp_f32_e32 v74, v74
	v_add_f32_e32 v121, v70, v121
	v_exp_f32_e32 v75, v75
	v_add_f32_e32 v121, v71, v121
	v_exp_f32_e32 v76, v76
	v_exp_f32_e32 v77, v77
	v_exp_f32_e32 v78, v78
	v_exp_f32_e32 v79, v79
	v_cvt_pk_bf16_f32 v64, v64, v65
	v_cvt_pk_bf16_f32 v65, v66, v67
	v_cvt_pk_bf16_f32 v66, v68, v69
	v_cvt_pk_bf16_f32 v67, v70, v71
	v_cvt_pk_bf16_f32 v68, v72, v73
	v_cvt_pk_bf16_f32 v69, v74, v75
	v_cvt_pk_bf16_f32 v70, v76, v77
	v_cvt_pk_bf16_f32 v71, v78, v79
	v_add_f32_e32 v72, v72, v121
	s_waitcnt lgkmcnt(0)
	s_setprio 2
	s_waitcnt vmcnt(3)
	s_barrier
	v_mfma_f32_32x32x16_bf16 v[0:15], v[64:67], v[144:147], v[0:15]
	v_add_f32_e32 v72, v73, v72
	s_sub_i32 s74, s0, s47
	s_cmp_lt_u32 s74, s100
	v_mfma_f32_32x32x16_bf16 v[48:63], v[64:67], v[152:155], v[48:63]
	v_add_f32_e32 v72, v74, v72
	v_mfma_f32_32x32x16_bf16 v[16:31], v[64:67], v[162:165], v[16:31]
	v_add_f32_e32 v72, v75, v72
	v_mfma_f32_32x32x16_bf16 v[32:47], v[64:67], v[170:173], v[32:47]
	v_add_f32_e32 v72, v76, v72
	v_mfma_f32_32x32x16_bf16 v[0:15], v[68:71], v[148:151], v[0:15]
	v_add_f32_e32 v72, v77, v72
	v_mfma_f32_32x32x16_bf16 v[48:63], v[68:71], v[156:159], v[48:63]
	v_add_f32_e32 v72, v78, v72
	v_mfma_f32_32x32x16_bf16 v[16:31], v[68:71], v[166:169], v[16:31]
	v_add_f32_e32 v72, v79, v72
	v_mfma_f32_32x32x16_bf16 v[32:47], v[68:71], v[174:177], v[32:47]
	v_add_f32_e32 v120, v120, v72
	v_mfma_f32_32x32x16_bf16 v[64:79], v[124:127], v[92:95], 0
	v_mfma_f32_32x32x16_bf16 v[64:79], v[132:135], v[88:91], v[64:79]
	v_mfma_f32_32x32x16_bf16 v[64:79], v[136:139], v[84:87], v[64:79]
	v_mfma_f32_32x32x16_bf16 v[64:79], v[140:143], v[80:83], v[64:79]
	s_cbranch_scc1 .Lhw_d1_b_dtd1bias2

; #define SBAR() __builtin_amdgcn_sched_barrier(0)
; #define ATT_DMA_K(t) do { const bf16_t* kg_ = Kh + (size_t)(t) * 64 * LDK; LAS unsigned char* sb_ = lds + ((t) & 3) * KBUF; \
;     _Pragma("unroll") for (int i_ = 0; i_ < NKP; ++i_) __builtin_amdgcn_global_load_lds((const unsigned*)(kg_ + kgo[i_]), (LAS unsigned*)(sb_ + (wid + 8 * i_) * 1024), 16, 0, 0); } while (0)
; #define ATT_DMA_V(t, vs) do { const bf16_t* vg_ = Vh + (size_t)(t) * 64 * LDV; LAS unsigned char* sb_ = lds + V_OFF + (vs) * SHM_V; \
;     _Pragma("unroll") for (int i_ = 0; i_ < 2; ++i_) __builtin_amdgcn_global_load_lds((const unsigned*)(vg_ + vgo[i_]), (LAS unsigned*)(sb_ + (2 * wid + i_) * 1024), 16, 0, 0); } while (0)
; #define ATT_SEG(t) do { if constexpr (MODE != 0) { if (((t) == tL && tL > 0) || (t) == tR) { const float f_ = (t) == tR ? fR : fL; l_reg *= f_; \
;     _Pragma("unroll") for (int d = 0; d < 4; ++d) _Pragma("unroll") for (int r = 0; r < 16; ++r) o[d][r] *= f_; } } } while (0)
; #define ATT_TOP(N) do { asm volatile("s_waitcnt vmcnt(%0)" :: "n"(N) : "memory"); __builtin_amdgcn_s_barrier(); asm volatile("" ::: "memory"); } while (0)
; DI void expsum(f32x16& p, float& l_reg, bf16x8& pa0, bf16x8& pa1) {
; #pragma unroll
;     for (int r = 0; r < 16; ++r) p[r] = __builtin_amdgcn_exp2f(p[r]);
;     float ps = 0.f;
; #pragma unroll
;     for (int r = 0; r < 16; ++r) ps += p[r];
;     l_reg += ps; asm volatile("" : "+v"(l_reg));
;     ...
;     ATT_PK4(p, 0, pa0); ATT_PK4(p, 8, pa1);
;     ...
; }
; template <int DQK, int MODE, int LDQ, int LDK, int LDV> ...
;     ...
;     f32x16 pA, pB; bf16x8 pa0, pa1;
;     int v0 = 0, v1 = 1, v2 = 2;
;     ATT_TOP(NKP + 2);
;     { bf16x8 kf[NDA]; k_reads<DQK, 0, NDA>(kf, lds, 0, r32, hi); ATT_LGKM0(); qk_mma<0, NDA>(pA, kf, qr);
;       if constexpr (ND0 > NDA) { bf16x8 kg[ND0 - NDA]; k_reads<DQK, NDA, ND0>(kg, lds, 0, r32, hi); ATT_LGKM0(); qk_mma<NDA, ND0>(pA, kg, qr); }
;       ATT_BIAS(pA, 0, 0); }
;     if (wid >= 4) __builtin_amdgcn_s_setprio(1);
;     for (int j = 0; j < NT; ++j) {
;         if (j + 2 < NT) ATT_TOP(NKP + 2); else ATT_TOP(0);
;         if (j + 3 < NT) ATT_DMA_K(j + 3);
;         if (j + 2 < NT) ATT_DMA_V(j + 2, v2);
;         ATT_SEG(j); SBAR();
;         ATT_STEP(pA, pB, 0, v0, true, 1, j);
;         ATT_STEP(pB, pA, 1, v0, (j + 1 < NT), 0, j + 1);
;         { const int t_ = v0; v0 = v1; v1 = v2; v2 = t_; }
;     }
.LBB0_1955:
	s_add_i32 s3, s22, 0xffffc000
	s_and_b32 s3, s3, 0x6000
	v_add_u32_e32 v196, s3, v107
	v_add_u32_e32 v197, s3, v108
	v_add_u32_e32 v198, s3, v109
	v_add_u32_e32 v199, s3, v110
	ds_read_b128 v[124:127], v196
	ds_read_b128 v[132:135], v197
	ds_read_b128 v[136:139], v198
	ds_read_b128 v[140:143], v199
	ds_read_b64_tr_b16 v[144:145], v121 offset:0x2000
	ds_read_b64_tr_b16 v[146:147], v121 offset:0x2800
	ds_read_b64_tr_b16 v[148:149], v121 offset:0x3000
	ds_read_b64_tr_b16 v[150:151], v121 offset:0x3800
	ds_read_b64_tr_b16 v[152:153], v121 offset:0x2200
	ds_read_b64_tr_b16 v[154:155], v121 offset:0x2a00
	ds_read_b64_tr_b16 v[156:157], v121 offset:0x3200
	ds_read_b64_tr_b16 v[158:159], v121 offset:0x3a00
	ds_read_b64_tr_b16 v[162:163], v121 offset:0x2400
	ds_read_b64_tr_b16 v[164:165], v121 offset:0x2c00
	ds_read_b64_tr_b16 v[166:167], v121 offset:0x3400
	ds_read_b64_tr_b16 v[168:169], v121 offset:0x3c00
	ds_read_b64_tr_b16 v[170:171], v121 offset:0x2600
	ds_read_b64_tr_b16 v[172:173], v121 offset:0x2e00
	ds_read_b64_tr_b16 v[174:175], v121 offset:0x3600
	ds_read_b64_tr_b16 v[176:177], v121 offset:0x3e00
	s_setprio 1
	v_exp_f32_e32 v64, v64
	v_exp_f32_e32 v65, v65
	v_exp_f32_e32 v66, v66
	v_exp_f32_e32 v67, v67
	v_exp_f32_e32 v68, v68
	v_exp_f32_e32 v69, v69
	v_add_f32_e32 v121, v65, v64
	v_exp_f32_e32 v70, v70
	v_add_f32_e32 v121, v66, v121
	v_exp_f32_e32 v71, v71
	v_add_f32_e32 v121, v67, v121
	v_exp_f32_e32 v72, v72
	v_add_f32_e32 v121, v68, v121
	v_exp_f32_e32 v73, v73
	v_add_f32_e32 v121, v69, v121
	v_exp_f32_e32 v74, v74
	v_add_f32_e32 v121, v70, v121
	v_exp_f32_e32 v75, v75
	v_add_f32_e32 v121, v71, v121
	v_exp_f32_e32 v76, v76
	v_exp_f32_e32 v77, v77
	v_exp_f32_e32 v78, v78
	v_exp_f32_e32 v79, v79
	v_cvt_pk_bf16_f32 v64, v64, v65
	v_cvt_pk_bf16_f32 v65, v66, v67
	v_cvt_pk_bf16_f32 v66, v68, v69
	v_cvt_pk_bf16_f32 v67, v70, v71
	v_cvt_pk_bf16_f32 v68, v72, v73
	v_cvt_pk_bf16_f32 v69, v74, v75
	v_cvt_pk_bf16_f32 v70, v76, v77
	v_cvt_pk_bf16_f32 v71, v78, v79
	v_add_f32_e32 v72, v72, v121
	s_waitcnt lgkmcnt(0)
	s_setprio 2
	v_mfma_f32_32x32x16_bf16 v[0:15], v[64:67], v[144:147], v[0:15]
	v_add_f32_e32 v72, v73, v72
	s_sub_i32 s74, s0, s47
	s_cmp_lt_u32 s74, s100
	v_mfma_f32_32x32x16_bf16 v[48:63], v[64:67], v[152:155], v[48:63]
	v_add_f32_e32 v72, v74, v72
	v_mfma_f32_32x32x16_bf16 v[16:31], v[64:67], v[162:165], v[16:31]
	v_add_f32_e32 v72, v75, v72
	v_mfma_f32_32x32x16_bf16 v[32:47], v[64:67], v[170:173], v[32:47]
	v_add_f32_e32 v72, v76, v72
	v_mfma_f32_32x32x16_bf16 v[0:15], v[68:71], v[148:151], v[0:15]
	v_add_f32_e32 v72, v77, v72
	v_mfma_f32_32x32x16_bf16 v[48:63], v[68:71], v[156:159], v[48:63]
	v_add_f32_e32 v72, v78, v72
	v_mfma_f32_32x32x16_bf16 v[16:31], v[68:71], v[166:169], v[16:31]
	v_add_f32_e32 v72, v79, v72
	v_mfma_f32_32x32x16_bf16 v[32:47], v[68:71], v[174:177], v[32:47]
	v_add_f32_e32 v120, v120, v72
	v_mfma_f32_32x32x16_bf16 v[64:79], v[124:127], v[92:95], 0
	v_mfma_f32_32x32x16_bf16 v[64:79], v[132:135], v[88:91], v[64:79]
	v_mfma_f32_32x32x16_bf16 v[64:79], v[136:139], v[84:87], v[64:79]
	v_mfma_f32_32x32x16_bf16 v[64:79], v[140:143], v[80:83], v[64:79]
	s_cbranch_scc1 .Ldt_d1_bias2

; DI float bf2f(unsigned short h) { return __uint_as_float((unsigned)h << 16); }
; DI unsigned cvtpk(float lo, float hi) { unsigned r; asm volatile("v_cvt_pk_bf16_f32 %0, %1, %2" : "=v"(r) : "v"(lo), "v"(hi)); return r; }
; DI float swap_sum(float v) { auto rr = __builtin_amdgcn_permlane32_swap(__float_as_uint(v), __float_as_uint(v), false, false); return __uint_as_float(rr[0]) + __uint_as_float(rr[1]); }
; DI void expsum(f32x16& p, float& l_reg, bf16x8& pa0, bf16x8& pa1) {
; #pragma unroll
;     for (int r = 0; r < 16; ++r) p[r] = __builtin_amdgcn_exp2f(p[r]);
;     float ps = 0.f;
; #pragma unroll
;     for (int r = 0; r < 16; ++r) ps += p[r];
;     l_reg += ps; asm volatile("" : "+v"(l_reg));
;     ...
;     ATT_PK4(p, 0, pa0); ATT_PK4(p, 8, pa1);
;     ...
; }
; template <int DQK, int MODE, int LDQ, int LDK, int LDV> ...
;     ...
;     ATT_DMA_K(0); ATT_DMA_K(1); ATT_DMA_V(0, 0); ATT_DMA_K(2); ATT_DMA_V(1, 1);
;     bf16x8 qr[ND0];
;     { const bf16_t* Qw = Qb + (size_t)(wid * 32 + r32) * LDQ + hi * 8;
; #pragma unroll
;       for (int d0 = 0; d0 < ND0; ++d0) qr[d0] = *(const bf16x8*)(Qw + d0 * 16);
;       if constexpr (MODE == 0) {
;           float ss = 0.f;
; #pragma unroll
;           for (int d0 = 0; d0 < ND0; ++d0)
; #pragma unroll
;               for (int j = 0; j < 8; ++j) { const float f = bf2f((unsigned short)qr[d0][j]); ss += f * f; }
;           ss = swap_sum(ss);
;           const float rstd = rsqrtf(ss * (1.f / DQK) + EPS) * C;
; #pragma unroll
;           for (int d0 = 0; d0 < ND0; ++d0) { const float* g = gq + d0 * 16 + hi * 8;
;               { float f[8]; _Pragma("unroll") for (int j = 0; j < 8; ++j) f[j] = bf2f((unsigned short)qr[d0][j]) * rstd * g[j];
;                 u32x4 w = {cvtpk(f[0], f[1]), cvtpk(f[2], f[3]), cvtpk(f[4], f[5]), cvtpk(f[6], f[7])}; qr[d0] = __builtin_bit_cast(bf16x8, w); asm volatile("" ::: "memory"); } }
;       } }
;     const int qlo = q0 + wid * 32, qpos = qlo + r32;
;     const int tL = MODE == 0 ? 0 : (qlo >= 191 ? (qlo - 127) >> 6 : 0), tR = MODE == 0 ? NT : min(NT, (qlo + 222) >> 6);
;     float fL = 1.f, fR = 1.f; if constexpr (MODE != 0) { fL = __builtin_amdgcn_exp2f(bt[0]); fR = __builtin_amdgcn_exp2f(-bt[448]); }
;     ...
;     const int vbase = (int)(unsigned)(size_t)lds + V_OFF + v_rd_base(lane);
;     ...
;     constexpr int NDA = ND0 > 6 ? 6 : ND0;
.Lhw_mla_b_n1982:
	s_and_b32 s1, s43, 3
	s_mulk_i32 s1, 0x6000
	s_add_i32 s1, s49, s1
	s_setprio 0
	s_mov_b32 m0, s1
	s_mov_b32 s0, s5
	s_mov_b32 s5, s44
	s_mov_b32 s44, s4
	s_lshl_b32 s4, s4, 14
	global_load_lds_dwordx4 v136, s[34:35]
	s_add_i32 m0, s1, 0x2000
	s_add_i32 s4, s52, s4
	global_load_lds_dwordx4 v138, s[34:35]
	s_add_i32 m0, s1, 0x4000
	s_add_i32 s6, s4, 0x400
	global_load_lds_dwordx4 v140, s[34:35]
	s_mov_b32 m0, s4
	s_add_i32 s1, s43, -3
	global_load_lds_dwordx4 v144, s[34:35]
	s_mov_b32 m0, s6
	s_nop 0
	global_load_lds_dwordx4 v142, s[34:35]
	s_and_b32 s1, s1, 3
	s_mulk_i32 s1, 0x6000
	v_add_u32_e32 v246, s1, v158
	v_add_u32_e32 v250, v246, v151
	v_add_u32_e32 v251, v246, v149
	v_add_u32_e32 v252, v246, v148
	v_add_u32_e32 v253, v246, v147
	s_lshl_b32 s1, s0, 14
	ds_read_b128 v[190:193], v250 offset:12416
	ds_read_b128 v[194:197], v251 offset:12416
	ds_read_b128 v[174:177], v250 offset:12288
	ds_read_b128 v[178:181], v251 offset:12288
	ds_read_b128 v[182:185], v252 offset:12288
	ds_read_b128 v[186:189], v253 offset:12288
	v_add_u32_e32 v254, s1, v130
	ds_read_b64_tr_b16 v[198:199], v254 offset:0
	ds_read_b64_tr_b16 v[200:201], v254 offset:0x800
	ds_read_b64_tr_b16 v[202:203], v254 offset:0x1000
	ds_read_b64_tr_b16 v[204:205], v254 offset:0x1800
	ds_read_b64_tr_b16 v[206:207], v254 offset:0x200
	ds_read_b64_tr_b16 v[208:209], v254 offset:0xa00
	ds_read_b64_tr_b16 v[210:211], v254 offset:0x1200
	ds_read_b64_tr_b16 v[212:213], v254 offset:0x1a00
	ds_read_b64_tr_b16 v[214:215], v254 offset:0x400
	ds_read_b64_tr_b16 v[216:217], v254 offset:0xc00
	ds_read_b64_tr_b16 v[218:219], v254 offset:0x1400
	ds_read_b64_tr_b16 v[220:221], v254 offset:0x1c00
	ds_read_b64_tr_b16 v[222:223], v254 offset:0x600
	ds_read_b64_tr_b16 v[224:225], v254 offset:0xe00
	ds_read_b64_tr_b16 v[226:227], v254 offset:0x1600
	ds_read_b64_tr_b16 v[228:229], v254 offset:0x1e00
	s_setprio 1
	v_exp_f32_e32 v64, v64
	v_exp_f32_e32 v65, v65
	v_exp_f32_e32 v66, v66
	v_exp_f32_e32 v67, v67
	v_exp_f32_e32 v68, v68
	v_exp_f32_e32 v69, v69
	v_add_f32_e32 v230, v65, v64
	v_exp_f32_e32 v70, v70
	v_add_f32_e32 v230, v66, v230
	v_exp_f32_e32 v71, v71
	v_add_f32_e32 v230, v67, v230
	v_exp_f32_e32 v72, v72
	v_add_f32_e32 v230, v68, v230
	v_exp_f32_e32 v73, v73
	v_add_f32_e32 v230, v69, v230
	v_exp_f32_e32 v74, v74
	v_add_f32_e32 v230, v70, v230
	v_exp_f32_e32 v75, v75
	v_add_f32_e32 v230, v71, v230
	v_exp_f32_e32 v76, v76
	v_exp_f32_e32 v77, v77
	v_exp_f32_e32 v78, v78
	v_exp_f32_e32 v79, v79
	v_cvt_pk_bf16_f32 v64, v64, v65
	v_cvt_pk_bf16_f32 v65, v66, v67
	v_cvt_pk_bf16_f32 v66, v68, v69
	v_cvt_pk_bf16_f32 v67, v70, v71
	v_cvt_pk_bf16_f32 v68, v72, v73
	v_cvt_pk_bf16_f32 v69, v74, v75
	v_cvt_pk_bf16_f32 v70, v76, v77
	v_cvt_pk_bf16_f32 v71, v78, v79
	v_add_f32_e32 v72, v72, v230
	s_waitcnt lgkmcnt(0)
	ds_read_b128 v[230:233], v252 offset:12416
	ds_read_b128 v[234:237], v253 offset:12416
	ds_read_b128 v[238:241], v250 offset:12544
	ds_read_b128 v[242:245], v251 offset:12544
	ds_read_b128 v[246:249], v252 offset:12544
	ds_read_b128 v[250:253], v253 offset:12544
	s_setprio 2
	v_mfma_f32_32x32x16_bf16 v[48:63], v[64:67], v[198:201], v[48:63]
	v_add_f32_e32 v72, v73, v72
	v_mfma_f32_32x32x16_bf16 v[32:47], v[64:67], v[206:209], v[32:47]
	v_add_f32_e32 v72, v74, v72
	v_mfma_f32_32x32x16_bf16 v[16:31], v[64:67], v[214:217], v[16:31]
	v_add_f32_e32 v72, v75, v72
	v_mfma_f32_32x32x16_bf16 v[0:15], v[64:67], v[222:225], v[0:15]
	v_add_f32_e32 v72, v76, v72
	v_mfma_f32_32x32x16_bf16 v[48:63], v[68:71], v[202:205], v[48:63]
	v_add_f32_e32 v72, v77, v72
	v_mfma_f32_32x32x16_bf16 v[32:47], v[68:71], v[210:213], v[32:47]
	v_add_f32_e32 v72, v78, v72
	v_mfma_f32_32x32x16_bf16 v[16:31], v[68:71], v[218:221], v[16:31]
	v_add_f32_e32 v72, v79, v72
	v_mfma_f32_32x32x16_bf16 v[0:15], v[68:71], v[226:229], v[0:15]
	v_add_f32_e32 v173, v173, v72
	s_waitcnt lgkmcnt(0)
	v_mfma_f32_32x32x16_bf16 v[64:79], v[174:177], v[80:83], 0
	v_mfma_f32_32x32x16_bf16 v[64:79], v[178:181], v[84:87], v[64:79]
	v_mfma_f32_32x32x16_bf16 v[64:79], v[182:185], v[88:91], v[64:79]
	v_mfma_f32_32x32x16_bf16 v[64:79], v[186:189], v[92:95], v[64:79]
	v_mfma_f32_32x32x16_bf16 v[64:79], v[190:193], v[96:99], v[64:79]
	v_mfma_f32_32x32x16_bf16 v[64:79], v[194:197], v[100:103], v[64:79]
	v_mfma_f32_32x32x16_bf16 v[64:79], v[230:233], v[104:107], v[64:79]
	v_mfma_f32_32x32x16_bf16 v[64:79], v[234:237], v[108:111], v[64:79]
	v_mfma_f32_32x32x16_bf16 v[64:79], v[238:241], v[112:115], v[64:79]
	v_mfma_f32_32x32x16_bf16 v[64:79], v[242:245], v[116:119], v[64:79]
	v_mfma_f32_32x32x16_bf16 v[64:79], v[246:249], v[120:123], v[64:79]
	v_mfma_f32_32x32x16_bf16 v[64:79], v[250:253], v[124:127], v[64:79]
	s_setprio 0
	s_add_i32 s4, s43, -2
	s_and_b32 s4, s4, 3
	s_mulk_i32 s4, 0x6000
	v_add_u32_e32 v246, s4, v158
	v_add_u32_e32 v250, v246, v151
	v_add_u32_e32 v251, v246, v149
	v_add_u32_e32 v252, v246, v148
	v_add_u32_e32 v253, v246, v147
	ds_read_b128 v[190:193], v250 offset:128
	ds_read_b128 v[194:197], v251 offset:128
	ds_read_b128 v[174:177], v250
	ds_read_b128 v[178:181], v251
	ds_read_b128 v[182:185], v252
	ds_read_b128 v[186:189], v253
	ds_read_b64_tr_b16 v[198:199], v254 offset:0x2000
	ds_read_b64_tr_b16 v[200:201], v254 offset:0x2800
	ds_read_b64_tr_b16 v[202:203], v254 offset:0x3000
	ds_read_b64_tr_b16 v[204:205], v254 offset:0x3800
	ds_read_b64_tr_b16 v[206:207], v254 offset:0x2200
	ds_read_b64_tr_b16 v[208:209], v254 offset:0x2a00
	ds_read_b64_tr_b16 v[210:211], v254 offset:0x3200
	ds_read_b64_tr_b16 v[212:213], v254 offset:0x3a00
	ds_read_b64_tr_b16 v[214:215], v254 offset:0x2400
	ds_read_b64_tr_b16 v[216:217], v254 offset:0x2c00
	ds_read_b64_tr_b16 v[218:219], v254 offset:0x3400
	ds_read_b64_tr_b16 v[220:221], v254 offset:0x3c00
	ds_read_b64_tr_b16 v[222:223], v254 offset:0x2600
	ds_read_b64_tr_b16 v[224:225], v254 offset:0x2e00
	ds_read_b64_tr_b16 v[226:227], v254 offset:0x3600
	ds_read_b64_tr_b16 v[228:229], v254 offset:0x3e00
	s_setprio 1
	v_exp_f32_e32 v64, v64
	v_exp_f32_e32 v65, v65
	v_exp_f32_e32 v66, v66
	v_exp_f32_e32 v67, v67
	v_exp_f32_e32 v68, v68
	v_exp_f32_e32 v69, v69
	v_add_f32_e32 v230, v65, v64
	v_exp_f32_e32 v70, v70
	v_add_f32_e32 v230, v66, v230
	v_exp_f32_e32 v71, v71
	v_add_f32_e32 v230, v67, v230
	v_exp_f32_e32 v72, v72
	v_add_f32_e32 v230, v68, v230
	v_exp_f32_e32 v73, v73
	v_add_f32_e32 v230, v69, v230
	v_exp_f32_e32 v74, v74
	v_add_f32_e32 v230, v70, v230
	v_exp_f32_e32 v75, v75
	v_add_f32_e32 v230, v71, v230
	v_exp_f32_e32 v76, v76
	v_exp_f32_e32 v77, v77
	v_exp_f32_e32 v78, v78
	v_exp_f32_e32 v79, v79
	v_cvt_pk_bf16_f32 v64, v64, v65
	v_cvt_pk_bf16_f32 v65, v66, v67
	v_cvt_pk_bf16_f32 v66, v68, v69
	v_cvt_pk_bf16_f32 v67, v70, v71
	v_cvt_pk_bf16_f32 v68, v72, v73
	v_cvt_pk_bf16_f32 v69, v74, v75
	v_cvt_pk_bf16_f32 v70, v76, v77
	v_cvt_pk_bf16_f32 v71, v78, v79
	v_add_f32_e32 v72, v72, v230
	s_waitcnt lgkmcnt(0)
; #define SBAR() __builtin_amdgcn_sched_barrier(0)
; #define ATT_DMA_K(t) do { const bf16_t* kg_ = Kh + (size_t)(t) * 64 * LDK; LAS unsigned char* sb_ = lds + ((t) & 3) * KBUF; \
;     _Pragma("unroll") for (int i_ = 0; i_ < NKP; ++i_) __builtin_amdgcn_global_load_lds((const unsigned*)(kg_ + kgo[i_]), (LAS unsigned*)(sb_ + (wid + 8 * i_) * 1024), 16, 0, 0); } while (0)
; #define ATT_DMA_V(t, vs) do { const bf16_t* vg_ = Vh + (size_t)(t) * 64 * LDV; LAS unsigned char* sb_ = lds + V_OFF + (vs) * SHM_V; \
;     _Pragma("unroll") for (int i_ = 0; i_ < 2; ++i_) __builtin_amdgcn_global_load_lds((const unsigned*)(vg_ + vgo[i_]), (LAS unsigned*)(sb_ + (2 * wid + i_) * 1024), 16, 0, 0); } while (0)
; #define ATT_SEG(t) do { if constexpr (MODE != 0) { if (((t) == tL && tL > 0) || (t) == tR) { const float f_ = (t) == tR ? fR : fL; l_reg *= f_; \
;     _Pragma("unroll") for (int d = 0; d < 4; ++d) _Pragma("unroll") for (int r = 0; r < 16; ++r) o[d][r] *= f_; } } } while (0)
; #define ATT_TOP(N) do { asm volatile("s_waitcnt vmcnt(%0)" :: "n"(N) : "memory"); __builtin_amdgcn_s_barrier(); asm volatile("" ::: "memory"); } while (0)
; DI void expsum(f32x16& p, float& l_reg, bf16x8& pa0, bf16x8& pa1) {
; #pragma unroll
;     for (int r = 0; r < 16; ++r) p[r] = __builtin_amdgcn_exp2f(p[r]);
;     float ps = 0.f;
; #pragma unroll
;     for (int r = 0; r < 16; ++r) ps += p[r];
;     l_reg += ps; asm volatile("" : "+v"(l_reg));
;     ...
;     ATT_PK4(p, 0, pa0); ATT_PK4(p, 8, pa1);
;     ...
; }
; template <int DQK, int MODE, int LDQ, int LDK, int LDV> ...
;     ...
;     f32x16 pA, pB; bf16x8 pa0, pa1;
;     int v0 = 0, v1 = 1, v2 = 2;
;     ATT_TOP(NKP + 2);
;     { bf16x8 kf[NDA]; k_reads<DQK, 0, NDA>(kf, lds, 0, r32, hi); ATT_LGKM0(); qk_mma<0, NDA>(pA, kf, qr);
;       if constexpr (ND0 > NDA) { bf16x8 kg[ND0 - NDA]; k_reads<DQK, NDA, ND0>(kg, lds, 0, r32, hi); ATT_LGKM0(); qk_mma<NDA, ND0>(pA, kg, qr); }
;       ATT_BIAS(pA, 0, 0); }
;     if (wid >= 4) __builtin_amdgcn_s_setprio(1);
;     for (int j = 0; j < NT; ++j) {
;         if (j + 2 < NT) ATT_TOP(NKP + 2); else ATT_TOP(0);
;         if (j + 3 < NT) ATT_DMA_K(j + 3);
;         if (j + 2 < NT) ATT_DMA_V(j + 2, v2);
;         ATT_SEG(j); SBAR();
;         ATT_STEP(pA, pB, 0, v0, true, 1, j);
;         ATT_STEP(pB, pA, 1, v0, (j + 1 < NT), 0, j + 1);
;         { const int t_ = v0; v0 = v1; v1 = v2; v2 = t_; }
;     }
	ds_read_b128 v[230:233], v252 offset:128
	ds_read_b128 v[234:237], v253 offset:128
	ds_read_b128 v[238:241], v250 offset:256
	ds_read_b128 v[242:245], v251 offset:256
	ds_read_b128 v[246:249], v252 offset:256
	ds_read_b128 v[250:253], v253 offset:256
	s_setprio 2
	s_waitcnt vmcnt(5)
	s_barrier
	v_mfma_f32_32x32x16_bf16 v[48:63], v[64:67], v[198:201], v[48:63]
	v_add_f32_e32 v72, v73, v72
	v_mfma_f32_32x32x16_bf16 v[32:47], v[64:67], v[206:209], v[32:47]
	v_add_f32_e32 v72, v74, v72
	v_mfma_f32_32x32x16_bf16 v[16:31], v[64:67], v[214:217], v[16:31]
	v_add_f32_e32 v72, v75, v72
	v_mfma_f32_32x32x16_bf16 v[0:15], v[64:67], v[222:225], v[0:15]
	v_add_f32_e32 v72, v76, v72
	v_mfma_f32_32x32x16_bf16 v[48:63], v[68:71], v[202:205], v[48:63]
	v_add_f32_e32 v72, v77, v72
	v_mfma_f32_32x32x16_bf16 v[32:47], v[68:71], v[210:213], v[32:47]
	v_add_f32_e32 v72, v78, v72
	v_mfma_f32_32x32x16_bf16 v[16:31], v[68:71], v[218:221], v[16:31]
	v_add_f32_e32 v72, v79, v72
	v_mfma_f32_32x32x16_bf16 v[0:15], v[68:71], v[226:229], v[0:15]
	v_add_f32_e32 v173, v173, v72
	s_waitcnt lgkmcnt(0)
	v_mfma_f32_32x32x16_bf16 v[64:79], v[174:177], v[80:83], 0
	v_mfma_f32_32x32x16_bf16 v[64:79], v[178:181], v[84:87], v[64:79]
	v_mfma_f32_32x32x16_bf16 v[64:79], v[182:185], v[88:91], v[64:79]
	v_mfma_f32_32x32x16_bf16 v[64:79], v[186:189], v[92:95], v[64:79]
	v_mfma_f32_32x32x16_bf16 v[64:79], v[190:193], v[96:99], v[64:79]
	v_mfma_f32_32x32x16_bf16 v[64:79], v[194:197], v[100:103], v[64:79]
	v_mfma_f32_32x32x16_bf16 v[64:79], v[230:233], v[104:107], v[64:79]
	v_mfma_f32_32x32x16_bf16 v[64:79], v[234:237], v[108:111], v[64:79]
	v_mfma_f32_32x32x16_bf16 v[64:79], v[238:241], v[112:115], v[64:79]
	v_mfma_f32_32x32x16_bf16 v[64:79], v[242:245], v[116:119], v[64:79]
	v_mfma_f32_32x32x16_bf16 v[64:79], v[246:249], v[120:123], v[64:79]
	v_mfma_f32_32x32x16_bf16 v[64:79], v[250:253], v[124:127], v[64:79]
	s_add_i32 s43, s43, 1
	v_add_u32_e32 v136, s36, v136
	v_add_u32_e32 v138, s36, v138
	v_add_u32_e32 v140, s36, v140
	v_add_u32_e32 v142, s38, v142
	v_add_u32_e32 v144, s38, v144
	s_cmp_eq_u32 s43, 64
	s_mov_b32 s4, s0
	s_cbranch_scc0 .Lhw_mla_b_n1982
	s_branch .Lhw_mla_exit
.LBB0_1982:
	s_and_b32 s1, s43, 3
	s_mulk_i32 s1, 0x6000
	s_add_i32 s1, s49, s1
	s_waitcnt vmcnt(5)
	s_barrier
	s_setprio 0
	s_mov_b32 m0, s1
	s_mov_b32 s0, s5
	s_mov_b32 s5, s44
	s_mov_b32 s44, s4
	s_lshl_b32 s4, s4, 14
	global_load_lds_dwordx4 v136, s[34:35]
	s_add_i32 m0, s1, 0x2000
	s_add_i32 s4, s52, s4
	global_load_lds_dwordx4 v138, s[34:35]
	s_add_i32 m0, s1, 0x4000
	s_add_i32 s6, s4, 0x400
	global_load_lds_dwordx4 v140, s[34:35]
	s_mov_b32 m0, s4
	s_add_i32 s1, s43, -3
	global_load_lds_dwordx4 v144, s[34:35]
	s_mov_b32 m0, s6
	s_nop 0
	global_load_lds_dwordx4 v142, s[34:35]
	s_and_b32 s1, s1, 3
	s_mulk_i32 s1, 0x6000
	v_add_u32_e32 v246, s1, v158
	v_add_u32_e32 v250, v246, v151
	v_add_u32_e32 v251, v246, v149
	v_add_u32_e32 v252, v246, v148
	v_add_u32_e32 v253, v246, v147
	s_lshl_b32 s1, s0, 14
	ds_read_b128 v[190:193], v250 offset:12416
	ds_read_b128 v[194:197], v251 offset:12416
	ds_read_b128 v[174:177], v250 offset:12288
	ds_read_b128 v[178:181], v251 offset:12288
	ds_read_b128 v[182:185], v252 offset:12288
	ds_read_b128 v[186:189], v253 offset:12288
	v_add_u32_e32 v254, s1, v130
	ds_read_b64_tr_b16 v[198:199], v254 offset:0
	ds_read_b64_tr_b16 v[200:201], v254 offset:0x800
	ds_read_b64_tr_b16 v[202:203], v254 offset:0x1000
	ds_read_b64_tr_b16 v[204:205], v254 offset:0x1800
	ds_read_b64_tr_b16 v[206:207], v254 offset:0x200
	ds_read_b64_tr_b16 v[208:209], v254 offset:0xa00
	ds_read_b64_tr_b16 v[210:211], v254 offset:0x1200
	ds_read_b64_tr_b16 v[212:213], v254 offset:0x1a00
	ds_read_b64_tr_b16 v[214:215], v254 offset:0x400
	ds_read_b64_tr_b16 v[216:217], v254 offset:0xc00
	ds_read_b64_tr_b16 v[218:219], v254 offset:0x1400
	ds_read_b64_tr_b16 v[220:221], v254 offset:0x1c00
	ds_read_b64_tr_b16 v[222:223], v254 offset:0x600
	ds_read_b64_tr_b16 v[224:225], v254 offset:0xe00
	ds_read_b64_tr_b16 v[226:227], v254 offset:0x1600
	ds_read_b64_tr_b16 v[228:229], v254 offset:0x1e00
	s_setprio 1
	v_exp_f32_e32 v64, v64
	v_exp_f32_e32 v65, v65
	v_exp_f32_e32 v66, v66
	v_exp_f32_e32 v67, v67
	v_exp_f32_e32 v68, v68
	v_exp_f32_e32 v69, v69
	v_add_f32_e32 v230, v65, v64
	v_exp_f32_e32 v70, v70
	v_add_f32_e32 v230, v66, v230
	v_exp_f32_e32 v71, v71
	v_add_f32_e32 v230, v67, v230
	v_exp_f32_e32 v72, v72
	v_add_f32_e32 v230, v68, v230
	v_exp_f32_e32 v73, v73
	v_add_f32_e32 v230, v69, v230
	v_exp_f32_e32 v74, v74
	v_add_f32_e32 v230, v70, v230
	v_exp_f32_e32 v75, v75
	v_add_f32_e32 v230, v71, v230
	v_exp_f32_e32 v76, v76
	v_exp_f32_e32 v77, v77
	v_exp_f32_e32 v78, v78
	v_exp_f32_e32 v79, v79
	v_cvt_pk_bf16_f32 v64, v64, v65
	v_cvt_pk_bf16_f32 v65, v66, v67
	v_cvt_pk_bf16_f32 v66, v68, v69
	v_cvt_pk_bf16_f32 v67, v70, v71
	v_cvt_pk_bf16_f32 v68, v72, v73
	v_cvt_pk_bf16_f32 v69, v74, v75
	v_cvt_pk_bf16_f32 v70, v76, v77
	v_cvt_pk_bf16_f32 v71, v78, v79
	v_add_f32_e32 v72, v72, v230
	s_waitcnt lgkmcnt(0)
	ds_read_b128 v[230:233], v252 offset:12416
	ds_read_b128 v[234:237], v253 offset:12416
	ds_read_b128 v[238:241], v250 offset:12544
	ds_read_b128 v[242:245], v251 offset:12544
	ds_read_b128 v[246:249], v252 offset:12544
	ds_read_b128 v[250:253], v253 offset:12544
	s_setprio 2
	v_mfma_f32_32x32x16_bf16 v[48:63], v[64:67], v[198:201], v[48:63]
	v_add_f32_e32 v72, v73, v72
	v_mfma_f32_32x32x16_bf16 v[32:47], v[64:67], v[206:209], v[32:47]
	v_add_f32_e32 v72, v74, v72
	v_mfma_f32_32x32x16_bf16 v[16:31], v[64:67], v[214:217], v[16:31]
	v_add_f32_e32 v72, v75, v72
	v_mfma_f32_32x32x16_bf16 v[0:15], v[64:67], v[222:225], v[0:15]
	v_add_f32_e32 v72, v76, v72
	v_mfma_f32_32x32x16_bf16 v[48:63], v[68:71], v[202:205], v[48:63]
	v_add_f32_e32 v72, v77, v72
	v_mfma_f32_32x32x16_bf16 v[32:47], v[68:71], v[210:213], v[32:47]
	v_add_f32_e32 v72, v78, v72
	v_mfma_f32_32x32x16_bf16 v[16:31], v[68:71], v[218:221], v[16:31]
	v_add_f32_e32 v72, v79, v72
	v_mfma_f32_32x32x16_bf16 v[0:15], v[68:71], v[226:229], v[0:15]
	v_add_f32_e32 v173, v173, v72
	s_waitcnt lgkmcnt(0)
; #define SBAR() __builtin_amdgcn_sched_barrier(0)
; #define ATT_DMA_K(t) do { const bf16_t* kg_ = Kh + (size_t)(t) * 64 * LDK; LAS unsigned char* sb_ = lds + ((t) & 3) * KBUF; \
;     _Pragma("unroll") for (int i_ = 0; i_ < NKP; ++i_) __builtin_amdgcn_global_load_lds((const unsigned*)(kg_ + kgo[i_]), (LAS unsigned*)(sb_ + (wid + 8 * i_) * 1024), 16, 0, 0); } while (0)
; #define ATT_DMA_V(t, vs) do { const bf16_t* vg_ = Vh + (size_t)(t) * 64 * LDV; LAS unsigned char* sb_ = lds + V_OFF + (vs) * SHM_V; \
;     _Pragma("unroll") for (int i_ = 0; i_ < 2; ++i_) __builtin_amdgcn_global_load_lds((const unsigned*)(vg_ + vgo[i_]), (LAS unsigned*)(sb_ + (2 * wid + i_) * 1024), 16, 0, 0); } while (0)
; #define ATT_SEG(t) do { if constexpr (MODE != 0) { if (((t) == tL && tL > 0) || (t) == tR) { const float f_ = (t) == tR ? fR : fL; l_reg *= f_; \
;     _Pragma("unroll") for (int d = 0; d < 4; ++d) _Pragma("unroll") for (int r = 0; r < 16; ++r) o[d][r] *= f_; } } } while (0)
; #define ATT_TOP(N) do { asm volatile("s_waitcnt vmcnt(%0)" :: "n"(N) : "memory"); __builtin_amdgcn_s_barrier(); asm volatile("" ::: "memory"); } while (0)
; DI void expsum(f32x16& p, float& l_reg, bf16x8& pa0, bf16x8& pa1) {
; #pragma unroll
;     for (int r = 0; r < 16; ++r) p[r] = __builtin_amdgcn_exp2f(p[r]);
;     float ps = 0.f;
; #pragma unroll
;     for (int r = 0; r < 16; ++r) ps += p[r];
;     l_reg += ps; asm volatile("" : "+v"(l_reg));
;     ...
;     ATT_PK4(p, 0, pa0); ATT_PK4(p, 8, pa1);
;     ...
; }
; template <int DQK, int MODE, int LDQ, int LDK, int LDV> ...
;     ...
;     f32x16 pA, pB; bf16x8 pa0, pa1;
;     int v0 = 0, v1 = 1, v2 = 2;
;     ATT_TOP(NKP + 2);
;     { bf16x8 kf[NDA]; k_reads<DQK, 0, NDA>(kf, lds, 0, r32, hi); ATT_LGKM0(); qk_mma<0, NDA>(pA, kf, qr);
;       if constexpr (ND0 > NDA) { bf16x8 kg[ND0 - NDA]; k_reads<DQK, NDA, ND0>(kg, lds, 0, r32, hi); ATT_LGKM0(); qk_mma<NDA, ND0>(pA, kg, qr); }
;       ATT_BIAS(pA, 0, 0); }
;     if (wid >= 4) __builtin_amdgcn_s_setprio(1);
;     for (int j = 0; j < NT; ++j) {
;         if (j + 2 < NT) ATT_TOP(NKP + 2); else ATT_TOP(0);
;         if (j + 3 < NT) ATT_DMA_K(j + 3);
;         if (j + 2 < NT) ATT_DMA_V(j + 2, v2);
;         ATT_SEG(j); SBAR();
;         ATT_STEP(pA, pB, 0, v0, true, 1, j);
;         ATT_STEP(pB, pA, 1, v0, (j + 1 < NT), 0, j + 1);
;         { const int t_ = v0; v0 = v1; v1 = v2; v2 = t_; }
;     }
	v_mfma_f32_32x32x16_bf16 v[64:79], v[174:177], v[80:83], 0
	v_mfma_f32_32x32x16_bf16 v[64:79], v[178:181], v[84:87], v[64:79]
	v_mfma_f32_32x32x16_bf16 v[64:79], v[182:185], v[88:91], v[64:79]
	v_mfma_f32_32x32x16_bf16 v[64:79], v[186:189], v[92:95], v[64:79]
	v_mfma_f32_32x32x16_bf16 v[64:79], v[190:193], v[96:99], v[64:79]
	v_mfma_f32_32x32x16_bf16 v[64:79], v[194:197], v[100:103], v[64:79]
	v_mfma_f32_32x32x16_bf16 v[64:79], v[230:233], v[104:107], v[64:79]
	v_mfma_f32_32x32x16_bf16 v[64:79], v[234:237], v[108:111], v[64:79]
	v_mfma_f32_32x32x16_bf16 v[64:79], v[238:241], v[112:115], v[64:79]
	v_mfma_f32_32x32x16_bf16 v[64:79], v[242:245], v[116:119], v[64:79]
	v_mfma_f32_32x32x16_bf16 v[64:79], v[246:249], v[120:123], v[64:79]
	v_mfma_f32_32x32x16_bf16 v[64:79], v[250:253], v[124:127], v[64:79]
	s_setprio 0
	s_add_i32 s4, s43, -2
	s_and_b32 s4, s4, 3
	s_mulk_i32 s4, 0x6000
	v_add_u32_e32 v246, s4, v158
	v_add_u32_e32 v250, v246, v151
	v_add_u32_e32 v251, v246, v149
	v_add_u32_e32 v252, v246, v148
	v_add_u32_e32 v253, v246, v147
	ds_read_b128 v[190:193], v250 offset:128
	ds_read_b128 v[194:197], v251 offset:128
	ds_read_b128 v[174:177], v250
	ds_read_b128 v[178:181], v251
	ds_read_b128 v[182:185], v252
	ds_read_b128 v[186:189], v253
	ds_read_b64_tr_b16 v[198:199], v254 offset:0x2000
	ds_read_b64_tr_b16 v[200:201], v254 offset:0x2800
	ds_read_b64_tr_b16 v[202:203], v254 offset:0x3000
	ds_read_b64_tr_b16 v[204:205], v254 offset:0x3800
	ds_read_b64_tr_b16 v[206:207], v254 offset:0x2200
	ds_read_b64_tr_b16 v[208:209], v254 offset:0x2a00
	ds_read_b64_tr_b16 v[210:211], v254 offset:0x3200
	ds_read_b64_tr_b16 v[212:213], v254 offset:0x3a00
	ds_read_b64_tr_b16 v[214:215], v254 offset:0x2400
	ds_read_b64_tr_b16 v[216:217], v254 offset:0x2c00
	ds_read_b64_tr_b16 v[218:219], v254 offset:0x3400
	ds_read_b64_tr_b16 v[220:221], v254 offset:0x3c00
	ds_read_b64_tr_b16 v[222:223], v254 offset:0x2600
	ds_read_b64_tr_b16 v[224:225], v254 offset:0x2e00
	ds_read_b64_tr_b16 v[226:227], v254 offset:0x3600
	ds_read_b64_tr_b16 v[228:229], v254 offset:0x3e00
	s_setprio 1
	v_exp_f32_e32 v64, v64
	v_exp_f32_e32 v65, v65
	v_exp_f32_e32 v66, v66
	v_exp_f32_e32 v67, v67
	v_exp_f32_e32 v68, v68
	v_exp_f32_e32 v69, v69
	v_add_f32_e32 v230, v65, v64
	v_exp_f32_e32 v70, v70
	v_add_f32_e32 v230, v66, v230
	v_exp_f32_e32 v71, v71
	v_add_f32_e32 v230, v67, v230
	v_exp_f32_e32 v72, v72
	v_add_f32_e32 v230, v68, v230
	v_exp_f32_e32 v73, v73
	v_add_f32_e32 v230, v69, v230
	v_exp_f32_e32 v74, v74
	v_add_f32_e32 v230, v70, v230
	v_exp_f32_e32 v75, v75
	v_add_f32_e32 v230, v71, v230
	v_exp_f32_e32 v76, v76
	v_exp_f32_e32 v77, v77
	v_exp_f32_e32 v78, v78
	v_exp_f32_e32 v79, v79
	v_cvt_pk_bf16_f32 v64, v64, v65
	v_cvt_pk_bf16_f32 v65, v66, v67
	v_cvt_pk_bf16_f32 v66, v68, v69
	v_cvt_pk_bf16_f32 v67, v70, v71
	v_cvt_pk_bf16_f32 v68, v72, v73
	v_cvt_pk_bf16_f32 v69, v74, v75
	v_cvt_pk_bf16_f32 v70, v76, v77
	v_cvt_pk_bf16_f32 v71, v78, v79
	v_add_f32_e32 v72, v72, v230
	s_waitcnt lgkmcnt(0)
	ds_read_b128 v[230:233], v252 offset:128
	ds_read_b128 v[234:237], v253 offset:128
	ds_read_b128 v[238:241], v250 offset:256
	ds_read_b128 v[242:245], v251 offset:256
	ds_read_b128 v[246:249], v252 offset:256
	ds_read_b128 v[250:253], v253 offset:256
	s_setprio 2
	v_mfma_f32_32x32x16_bf16 v[48:63], v[64:67], v[198:201], v[48:63]
	v_add_f32_e32 v72, v73, v72
	v_mfma_f32_32x32x16_bf16 v[32:47], v[64:67], v[206:209], v[32:47]
	v_add_f32_e32 v72, v74, v72
	v_mfma_f32_32x32x16_bf16 v[16:31], v[64:67], v[214:217], v[16:31]
	v_add_f32_e32 v72, v75, v72
	v_mfma_f32_32x32x16_bf16 v[0:15], v[64:67], v[222:225], v[0:15]
	v_add_f32_e32 v72, v76, v72
	v_mfma_f32_32x32x16_bf16 v[48:63], v[68:71], v[202:205], v[48:63]
	v_add_f32_e32 v72, v77, v72
	v_mfma_f32_32x32x16_bf16 v[32:47], v[68:71], v[210:213], v[32:47]
	v_add_f32_e32 v72, v78, v72
	v_mfma_f32_32x32x16_bf16 v[16:31], v[68:71], v[218:221], v[16:31]
	v_add_f32_e32 v72, v79, v72
	v_mfma_f32_32x32x16_bf16 v[0:15], v[68:71], v[226:229], v[0:15]
	v_add_f32_e32 v173, v173, v72
	s_waitcnt lgkmcnt(0)
	v_mfma_f32_32x32x16_bf16 v[64:79], v[174:177], v[80:83], 0
	v_mfma_f32_32x32x16_bf16 v[64:79], v[178:181], v[84:87], v[64:79]
	v_mfma_f32_32x32x16_bf16 v[64:79], v[182:185], v[88:91], v[64:79]
	v_mfma_f32_32x32x16_bf16 v[64:79], v[186:189], v[92:95], v[64:79]
	v_mfma_f32_32x32x16_bf16 v[64:79], v[190:193], v[96:99], v[64:79]
	v_mfma_f32_32x32x16_bf16 v[64:79], v[194:197], v[100:103], v[64:79]
	v_mfma_f32_32x32x16_bf16 v[64:79], v[230:233], v[104:107], v[64:79]
	v_mfma_f32_32x32x16_bf16 v[64:79], v[234:237], v[108:111], v[64:79]
	v_mfma_f32_32x32x16_bf16 v[64:79], v[238:241], v[112:115], v[64:79]
	v_mfma_f32_32x32x16_bf16 v[64:79], v[242:245], v[116:119], v[64:79]
	v_mfma_f32_32x32x16_bf16 v[64:79], v[246:249], v[120:123], v[64:79]
	v_mfma_f32_32x32x16_bf16 v[64:79], v[250:253], v[124:127], v[64:79]
	s_add_i32 s43, s43, 1
	v_add_u32_e32 v136, s36, v136
	v_add_u32_e32 v138, s36, v138
	v_add_u32_e32 v140, s36, v140
	v_add_u32_e32 v142, s38, v142
	v_add_u32_e32 v144, s38, v144
	s_cmp_eq_u32 s43, 64
	s_mov_b32 s4, s0
	s_cbranch_scc0 .LBB0_1982
